# merged GEMM: first K iteration peeled for unit 0 only (C=0), accumulator zeroing removed; units 1,2 enter the loop directly with carried accumulators
# speedup vs baseline: 1.0041x; 1.0034x over previous
; #define PG8_WAIT_V(n) asm volatile("s_waitcnt vmcnt(" #n ")" ::: "memory")
; #define PG8_BAR __builtin_amdgcn_s_barrier()
;     const int tid = threadIdx.x, wid = __builtin_amdgcn_readfirstlane(tid >> 6), lane = tid & 63, wr = wid >> 2, wc = wid & 3, fr = lane & 15, fq = lane >> 4;
;     const int nt = K / BK;
;     unsigned voffA[2], voffB[2];
; #pragma unroll
;     for (int i = 0; i < 2; ++i) { int R, C; stage_rc(tid * 16 + i * 8192, R, C); const int Rb = Epi::PERM64 ? (64 * (R >> 5) + perm32(R & 31)) : Epi::PERM ? ((R & ~31) + perm32(R & 31)) : R;
;         voffA[i] = (unsigned)(R * K + C) * 2u; voffB[i] = (unsigned)(Rb * K + C) * 2u; }
;     const size_t kstep = (size_t)(BK * 2);
;     const size_t hstep = (size_t)HALF * K * 2;
;     const size_t hstepB = Epi::PERM64 ? (size_t)32 * K * 2 : hstep;
;     const unsigned ldsw = (unsigned)wid * 1024u;
;     const int aoff = lds_byte(wr * 64 + fr, fq * 8), boff = lds_byte(wc * 32 + fr, fq * 8);
;     ...
;     Unit cur, nxt; int ui = 0;
;     if (!S.next(0, cur)) return;
;     f32x4 acc[2][2][4][2];
;     if constexpr (!DE) {
; #pragma unroll
;     for (int a = 0; a < 2; ++a)
; #pragma unroll
;         for (int b = 0; b < 2; ++b)
; #pragma unroll
;             for (int m = 0; m < 4; ++m)
; #pragma unroll
;                 for (int n = 0; n < 2; ++n) acc[a][b][m][n] = (f32x4){0.f, 0.f, 0.f, 0.f};
;     }
;     bf16x8 At[4][2], B0[2][2], B1[2][2];
;     const char* cA = S.a_ptr(cur); const char* cB = S.b_ptr(cur);
;     S.a_ready(cur);
;     if constexpr (SP2) {
;         PG8_STAGE(PG8_SB(0, 0), cB, voffB); PG8_STAGE(PG8_SB(0, 1), cB + hstepB, voffB); PG8_STAGE(PG8_SA(0, 0), cA, voffA); PG8_STAGE(PG8_SA(0, 1), cA + hstep, voffA);
;         if (wr == 1) PG8_BAR;
;         PG8_WAIT_V(2); PG8_BAR;
;         PG8_STAGE(PG8_SB(1, 0), cB + kstep, voffB); PG8_STAGE(PG8_SA(1, 0), cA + kstep, voffA); PG8_STAGE(PG8_SB(1, 1), cB + hstepB + kstep, voffB);
;         PG8_WAIT_V(6); PG8_BAR;
;     } else {
;         PG8_STAGE(PG8_SB(0, 0), cB, voffB); PG8_STAGE(PG8_SA(0, 0), cA, voffA); PG8_STAGE(PG8_SB(0, 1), cB + hstepB, voffB); PG8_STAGE(PG8_SA(0, 1), cA + hstep, voffA);
;         if (wr == 1) PG8_BAR;
;         PG8_WAIT_V(4); PG8_BAR;
;         PG8_STAGE(PG8_SB(1, 0), cB + kstep, voffB); PG8_STAGE(PG8_SA(1, 0), cA + kstep, voffA); PG8_STAGE(PG8_SB(1, 1), cB + hstepB + kstep, voffB);
;         PG8_WAIT_V(6); PG8_BAR;
.LBB0_572:
	v_and_b32_e32 v3, 15, v0
	v_lshlrev_b32_e32 v4, 1, v2
	v_lshlrev_b32_e32 v5, 2, v0
	v_lshl_or_b32 v210, s8, 6, v3
	v_lshl_or_b32 v3, v3, 6, v4
	s_lshl_b32 s3, s8, 13
	v_and_b32_e32 v5, 32, v5
	v_bitop3_b32 v3, v3, s3, v5 bitop3:0xde
	s_lshl_b32 s3, s9, 5
	s_and_b32 s3, s3, 0x60
	v_lshlrev_b32_e32 v6, 6, v0
	s_movk_i32 s5, 0x3c0
	v_and_or_b32 v4, v6, s5, v4
	s_lshl_b32 s5, s3, 7
	s_add_u32 s8, s22, 0x80
	v_bitop3_b32 v211, s5, v4, v5 bitop3:0xf6
	s_addc_u32 s9, s23, 0
	v_mov_b32_e32 v4, v195
	s_waitcnt vmcnt(2)
	s_barrier
	s_add_i32 m0, s31, 0x18000
	v_or_b32_e32 v194, s3, v2
	global_load_lds_dwordx4 v4, s[8:9]
	v_mov_b32_e32 v4, v209
	s_add_i32 m0, s31, 0x1a000
	global_load_lds_dwordx4 v4, s[8:9]
	s_add_u32 s8, s20, 0x80
	s_addc_u32 s9, s21, 0
	v_mov_b32_e32 v4, v1
	s_add_i32 s36, s31, 0x8000
	s_mov_b32 m0, s36
	s_add_i32 s37, s31, 0xa000
	global_load_lds_dwordx4 v4, s[8:9]
	v_mov_b32_e32 v4, v208
	s_mov_b32 m0, s37
	v_add_u32_e32 v212, 0, v3
	global_load_lds_dwordx4 v4, s[8:9]
	s_add_u32 s8, s22, 0x20080
	s_addc_u32 s9, s23, 0
	v_mov_b32_e32 v4, v195
	s_add_i32 m0, s31, 0x1c000
	s_mov_b32 s44, 0
	global_load_lds_dwordx4 v4, s[8:9]
	v_mov_b32_e32 v4, v209
	s_add_i32 m0, s31, 0x1e000
	s_cmpk_lt_u32 s7, 0x100
	global_load_lds_dwordx4 v4, s[8:9]
	s_cselect_b64 s[8:9], -1, 0
	s_ashr_i32 s3, s90, 31
	s_lshr_b32 s3, s3, 29
	s_add_i32 s3, s90, s3
	s_and_b32 s5, s3, -8
	s_sub_i32 s5, s90, s5
	s_lshl_b32 s7, s5, 5
	s_ashr_i32 s3, s3, 3
	s_add_u32 s38, s60, 0x2000000
	s_addc_u32 s39, s61, 0
	s_cmp_lt_i32 s5, 0
	s_mul_i32 s5, s5, 33
	s_cselect_b32 s5, s5, s7
	s_add_i32 s3, s5, s3
	s_ashr_i32 s5, s3, 31
	s_lshr_b32 s5, s5, 28
	s_add_i32 s5, s3, s5
	s_ashr_i32 s7, s5, 4
	s_and_b32 s5, s5, -16
	s_sub_i32 s3, s3, s5
	s_bfe_i32 s5, s3, 0x80000
	s_bfe_u32 s5, s5, 0x2000d
	s_add_i32 s5, s3, s5
	s_lshl_b32 s40, s7, 2
	s_bfe_i32 s7, s5, 0x80000
	s_and_b32 s5, s5, 0xfc
	s_waitcnt vmcnt(6)
	s_sub_i32 s3, s3, s5
	s_sext_i32_i16 s7, s7
	s_sext_i32_i8 s3, s3
	s_add_i32 s40, s40, s3
	s_ashr_i32 s41, s7, 2
	s_add_i32 s42, 0, 0x10000
	s_add_i32 s43, 0, 0x14000
	s_mov_b64 s[16:17], s[20:21]
	s_barrier
	s_branch .LBB0_575

; #define PG8_STAGE(bufoff, gbase, voff) do { const char* gb_ = (const char*)(gbase); asm volatile("" : "+s"(gb_)); _Pragma("unroll") for (int _i = 0; _i < 2; ++_i) { unsigned vo_ = (voff)[_i]; asm volatile("" : "+v"(vo_)); \
;         __builtin_amdgcn_global_load_lds((const unsigned*)(gb_ + vo_), (PG8_LAS unsigned*)(lds + (bufoff) + ldsw + _i * 8192), 16, 0, 0); } } while (0)
; #define PG8_LDA(dst, b, h) do { _Pragma("unroll") for (int m = 0; m < 4; ++m) _Pragma("unroll") for (int k = 0; k < 2; ++k) dst[m][k] = *(const PG8_LAS bf16x8*)(lds + PG8_SA(b, h) + aoff + m * 2048 + k * 1024); } while (0)
; #define PG8_LDB(dst, b, h) do { _Pragma("unroll") for (int n = 0; n < 2; ++n) _Pragma("unroll") for (int k = 0; k < 2; ++k) dst[n][k] = *(const PG8_LAS bf16x8*)(lds + PG8_SB(b, h) + boff + n * 2048 + k * 1024); } while (0)
; #define PG8_MMA(ai, bj, At, Bt) do { __builtin_amdgcn_s_setprio(1); _Pragma("unroll") for (int m = 0; m < 4; ++m) _Pragma("unroll") for (int n = 0; n < 2; ++n) _Pragma("unroll") for (int k = 0; k < 2; ++k) \
;         acc[ai][bj][m][n] = __builtin_amdgcn_mfma_f32_16x16x32_bf16(Bt[n][k], At[m][k], acc[ai][bj][m][n], 0, 0, 0); __builtin_amdgcn_s_setprio(0); } while (0)
; #define PG8_WAIT_V(n) asm volatile("s_waitcnt vmcnt(" #n ")" ::: "memory")
; #define PG8_WAIT_L(n) asm volatile("s_waitcnt lgkmcnt(" #n ")" ::: "memory")
;     ...
;         for (int t = 0; t < nt; t += 2) {
;             const bool last = (t == nt - 2);
;             if (GP && t == 2) gp1 = __builtin_amdgcn_s_memrealtime();
;             const char* a1 = cA + (size_t)(t + 1) * kstep;
;             const char* a2 = last ? nA : cA + (size_t)(t + 2) * kstep; const char* b2 = last ? nB : cB + (size_t)(t + 2) * kstep;
;             const char* a3 = a2 + kstep; const char* b3 = b2 + kstep;
;             if (last && has_next) S.a_ready(nxt);
;             if constexpr (SP2) {
;             PG8_LDB(B0, 0, 0); PG8_LDB(B1, 0, 1); PG8_SCHED; PG8_LDA(At, 0, 0); PG8_STAGE(PG8_SA(1, 1), a1 + hstep, voffA);
;             PG8_WAIT_V(8); PG8_WAIT_L(0); PG8_BAR; PG8_MMA(0, 0, At, B0); PG8_MMA(0, 1, At, B1); PG8_BAR; PG8_SCHED;
;             PG8_LDA(At, 0, 1); PG8_STAGE(PG8_SB(0, 0), b2, voffB); PG8_STAGE(PG8_SB(0, 1), b2 + hstepB, voffB); PG8_STAGE(PG8_SA(0, 0), a2, voffA);
;             PG8_WAIT_V(8); PG8_WAIT_L(0); PG8_BAR; PG8_MMA(1, 0, At, B0); PG8_MMA(1, 1, At, B1); PG8_BAR; PG8_SCHED;
.LBB0_577:
	s_and_b64 s[18:19], s[24:25], exec
	s_cselect_b32 s12, s41, s12
	s_ashr_i32 s13, s12, 31
	s_lshl_b64 s[18:19], s[10:11], 20
	s_lshl_b64 s[26:27], s[12:13], 18
	s_add_u32 s3, s48, s18
	s_addc_u32 s5, s49, s19
	s_add_u32 s18, s3, s26
	s_addc_u32 s19, s5, s27
	s_and_b64 s[24:25], s[24:25], exec
	s_cselect_b32 s3, s19, s23
	s_cselect_b32 s5, s18, s22
	s_add_u32 s7, s22, 0x100
	s_addc_u32 s11, s23, 0
	s_mov_b32 s13, -2
	s_cmp_lg_u32 s44, 0
	s_cbranch_scc1 .LBB0_578
	v_add_u32_e32 v142, s42, v211
	v_add_u32_e32 v158, s43, v211
	ds_read_b128 v[130:133], v142
	ds_read_b128 v[134:137], v142 offset:1024
	ds_read_b128 v[138:141], v142 offset:2048
	ds_read_b128 v[142:145], v142 offset:3072
	ds_read_b128 v[146:149], v158
	ds_read_b128 v[150:153], v158 offset:1024
	ds_read_b128 v[154:157], v158 offset:2048
	ds_read_b128 v[158:161], v158 offset:3072
	s_add_u32 s22, s20, 0x100
	s_addc_u32 s23, s21, 0
	s_cmp_eq_u32 s13, 4
	s_cselect_b32 s28, s16, s22
	s_cselect_b32 s29, s17, s23
	s_cselect_b32 s26, s5, s7
	s_cselect_b32 s27, s3, s11
	s_add_u32 s24, s28, 0x80
	s_addc_u32 s25, s29, 0
	s_add_u32 s20, s20, 0x20080
	s_addc_u32 s21, s21, 0
	v_mov_b32_e32 v196, v1
	ds_read_b128 v[162:165], v212
	ds_read_b128 v[166:169], v212 offset:1024
	ds_read_b128 v[170:173], v212 offset:2048
	s_waitcnt lgkmcnt(10)
	ds_read_b128 v[174:177], v212 offset:3072
	ds_read_b128 v[178:181], v212 offset:4096
	ds_read_b128 v[182:185], v212 offset:5120
	ds_read_b128 v[186:189], v212 offset:6144
	ds_read_b128 v[190:193], v212 offset:7168
	s_add_i32 m0, s31, 0xc000
	s_nop 0
	global_load_lds_dwordx4 v196, s[20:21]
	v_mov_b32_e32 v196, v208
	s_add_i32 m0, s31, 0xe000
	s_nop 0
	global_load_lds_dwordx4 v196, s[20:21]
	s_waitcnt vmcnt(8)
	s_waitcnt lgkmcnt(0)
	s_barrier
	s_setprio 1
	v_mfma_f32_16x16x32_bf16 v[126:129], v[130:133], v[162:165], 0
	v_mfma_f32_16x16x32_bf16 v[122:125], v[138:141], v[162:165], 0
	v_mfma_f32_16x16x32_bf16 v[118:121], v[130:133], v[170:173], 0
	v_mfma_f32_16x16x32_bf16 v[114:117], v[138:141], v[170:173], 0
	s_waitcnt lgkmcnt(0)
	v_mfma_f32_16x16x32_bf16 v[110:113], v[130:133], v[178:181], 0
	v_mfma_f32_16x16x32_bf16 v[106:109], v[138:141], v[178:181], 0
	v_mfma_f32_16x16x32_bf16 v[102:105], v[130:133], v[186:189], 0
	v_mfma_f32_16x16x32_bf16 v[98:101], v[138:141], v[186:189], 0
	v_mfma_f32_16x16x32_bf16 v[126:129], v[134:137], v[166:169], v[126:129]
	v_mfma_f32_16x16x32_bf16 v[122:125], v[142:145], v[166:169], v[122:125]
	v_mfma_f32_16x16x32_bf16 v[118:121], v[134:137], v[174:177], v[118:121]
	v_mfma_f32_16x16x32_bf16 v[114:117], v[142:145], v[174:177], v[114:117]
	v_mfma_f32_16x16x32_bf16 v[110:113], v[134:137], v[182:185], v[110:113]
	v_mfma_f32_16x16x32_bf16 v[106:109], v[142:145], v[182:185], v[106:109]
	v_mfma_f32_16x16x32_bf16 v[102:105], v[134:137], v[190:193], v[102:105]
	v_mfma_f32_16x16x32_bf16 v[98:101], v[142:145], v[190:193], v[98:101]
	s_setprio 0
	s_setprio 1
	v_mfma_f32_16x16x32_bf16 v[94:97], v[146:149], v[162:165], 0
	v_mfma_f32_16x16x32_bf16 v[90:93], v[154:157], v[162:165], 0
	v_mfma_f32_16x16x32_bf16 v[86:89], v[146:149], v[170:173], 0
	v_mfma_f32_16x16x32_bf16 v[82:85], v[154:157], v[170:173], 0
	v_mfma_f32_16x16x32_bf16 v[78:81], v[146:149], v[178:181], 0
	v_mfma_f32_16x16x32_bf16 v[74:77], v[154:157], v[178:181], 0
	v_mfma_f32_16x16x32_bf16 v[70:73], v[146:149], v[186:189], 0
	v_mfma_f32_16x16x32_bf16 v[62:65], v[154:157], v[186:189], 0
	v_mfma_f32_16x16x32_bf16 v[94:97], v[150:153], v[166:169], v[94:97]
	v_mfma_f32_16x16x32_bf16 v[90:93], v[158:161], v[166:169], v[90:93]
	v_mfma_f32_16x16x32_bf16 v[86:89], v[150:153], v[174:177], v[86:89]
	v_mfma_f32_16x16x32_bf16 v[82:85], v[158:161], v[174:177], v[82:85]
	v_mfma_f32_16x16x32_bf16 v[78:81], v[150:153], v[182:185], v[78:81]
	v_mfma_f32_16x16x32_bf16 v[74:77], v[158:161], v[182:185], v[74:77]
	v_mfma_f32_16x16x32_bf16 v[70:73], v[150:153], v[190:193], v[70:73]
	v_mfma_f32_16x16x32_bf16 v[62:65], v[158:161], v[190:193], v[62:65]
	s_setprio 0
	s_barrier
	s_mov_b64 s[20:21], s[26:27]
	v_mov_b32_e32 v196, v195
	s_add_i32 s15, s42, s30
	ds_read_b128 v[162:165], v212 offset:16384
	ds_read_b128 v[166:169], v212 offset:17408
	ds_read_b128 v[170:173], v212 offset:18432
	ds_read_b128 v[174:177], v212 offset:19456
	ds_read_b128 v[178:181], v212 offset:20480
	ds_read_b128 v[182:185], v212 offset:21504
	ds_read_b128 v[186:189], v212 offset:22528
	ds_read_b128 v[190:193], v212 offset:23552
	s_mov_b32 m0, s15
	s_nop 0
	global_load_lds_dwordx4 v196, s[20:21]
	v_mov_b32_e32 v196, v209
	s_add_i32 m0, s15, 0x2000
	s_nop 0
	global_load_lds_dwordx4 v196, s[20:21]
	s_add_u32 s20, s26, 0x20000
	s_addc_u32 s21, s27, 0
	v_mov_b32_e32 v196, v195
	s_add_i32 s15, s43, s30
	s_mov_b32 m0, s15
	s_nop 0
	global_load_lds_dwordx4 v196, s[20:21]
	v_mov_b32_e32 v196, v209
	s_add_i32 m0, s15, 0x2000
	s_nop 0
	global_load_lds_dwordx4 v196, s[20:21]
	s_mov_b64 s[20:21], s[28:29]
	v_mov_b32_e32 v196, v1
	s_mov_b32 m0, s31
	s_nop 0
	global_load_lds_dwordx4 v196, s[20:21]
	v_mov_b32_e32 v196, v208
	s_mov_b32 m0, s33
	s_nop 0
	global_load_lds_dwordx4 v196, s[20:21]
	s_waitcnt vmcnt(8)
	s_waitcnt lgkmcnt(0)
	s_barrier
; #define PG8_STAGE(bufoff, gbase, voff) do { const char* gb_ = (const char*)(gbase); asm volatile("" : "+s"(gb_)); _Pragma("unroll") for (int _i = 0; _i < 2; ++_i) { unsigned vo_ = (voff)[_i]; asm volatile("" : "+v"(vo_)); \
;         __builtin_amdgcn_global_load_lds((const unsigned*)(gb_ + vo_), (PG8_LAS unsigned*)(lds + (bufoff) + ldsw + _i * 8192), 16, 0, 0); } } while (0)
; #define PG8_LDA(dst, b, h) do { _Pragma("unroll") for (int m = 0; m < 4; ++m) _Pragma("unroll") for (int k = 0; k < 2; ++k) dst[m][k] = *(const PG8_LAS bf16x8*)(lds + PG8_SA(b, h) + aoff + m * 2048 + k * 1024); } while (0)
; #define PG8_LDB(dst, b, h) do { _Pragma("unroll") for (int n = 0; n < 2; ++n) _Pragma("unroll") for (int k = 0; k < 2; ++k) dst[n][k] = *(const PG8_LAS bf16x8*)(lds + PG8_SB(b, h) + boff + n * 2048 + k * 1024); } while (0)
; #define PG8_MMA(ai, bj, At, Bt) do { __builtin_amdgcn_s_setprio(1); _Pragma("unroll") for (int m = 0; m < 4; ++m) _Pragma("unroll") for (int n = 0; n < 2; ++n) _Pragma("unroll") for (int k = 0; k < 2; ++k) \
;         acc[ai][bj][m][n] = __builtin_amdgcn_mfma_f32_16x16x32_bf16(Bt[n][k], At[m][k], acc[ai][bj][m][n], 0, 0, 0); __builtin_amdgcn_s_setprio(0); } while (0)
; #define PG8_WAIT_V(n) asm volatile("s_waitcnt vmcnt(" #n ")" ::: "memory")
; #define PG8_WAIT_L(n) asm volatile("s_waitcnt lgkmcnt(" #n ")" ::: "memory")
; #define PG8_BAR __builtin_amdgcn_s_barrier()
; #define PG8_SCHED __builtin_amdgcn_sched_barrier(0)
;     ...
;             PG8_LDA(At, 0, 1); PG8_STAGE(PG8_SB(0, 0), b2, voffB); PG8_STAGE(PG8_SB(0, 1), b2 + hstepB, voffB); PG8_STAGE(PG8_SA(0, 0), a2, voffA);
;             PG8_WAIT_V(8); PG8_WAIT_L(0); PG8_BAR; PG8_MMA(1, 0, At, B0); PG8_MMA(1, 1, At, B1); PG8_BAR; PG8_SCHED;
;             PG8_LDB(B0, 1, 0); PG8_LDB(B1, 1, 1); PG8_SCHED; PG8_LDA(At, 1, 0); PG8_STAGE(PG8_SA(0, 1), a2 + hstep, voffA);
;             PG8_WAIT_V(8); PG8_WAIT_L(0); PG8_BAR; PG8_MMA(0, 0, At, B0); PG8_MMA(0, 1, At, B1); PG8_BAR; PG8_SCHED;
	s_setprio 1
	s_waitcnt lgkmcnt(0)
	v_mfma_f32_16x16x32_bf16 v[66:69], v[130:133], v[162:165], 0
	v_mfma_f32_16x16x32_bf16 v[58:61], v[138:141], v[162:165], 0
	v_mfma_f32_16x16x32_bf16 v[54:57], v[130:133], v[170:173], 0
	v_mfma_f32_16x16x32_bf16 v[50:53], v[138:141], v[170:173], 0
	v_mfma_f32_16x16x32_bf16 v[46:49], v[130:133], v[178:181], 0
	v_mfma_f32_16x16x32_bf16 v[42:45], v[138:141], v[178:181], 0
	v_mfma_f32_16x16x32_bf16 v[38:41], v[130:133], v[186:189], 0
	v_mfma_f32_16x16x32_bf16 v[34:37], v[138:141], v[186:189], 0
	v_mfma_f32_16x16x32_bf16 v[66:69], v[134:137], v[166:169], v[66:69]
	v_mfma_f32_16x16x32_bf16 v[58:61], v[142:145], v[166:169], v[58:61]
	v_mfma_f32_16x16x32_bf16 v[54:57], v[134:137], v[174:177], v[54:57]
	v_mfma_f32_16x16x32_bf16 v[50:53], v[142:145], v[174:177], v[50:53]
	v_mfma_f32_16x16x32_bf16 v[46:49], v[134:137], v[182:185], v[46:49]
	v_mfma_f32_16x16x32_bf16 v[42:45], v[142:145], v[182:185], v[42:45]
	v_mfma_f32_16x16x32_bf16 v[38:41], v[134:137], v[190:193], v[38:41]
	v_mfma_f32_16x16x32_bf16 v[34:37], v[142:145], v[190:193], v[34:37]
	s_setprio 0
	s_setprio 1
	v_mfma_f32_16x16x32_bf16 v[30:33], v[146:149], v[162:165], 0
	v_mfma_f32_16x16x32_bf16 v[26:29], v[154:157], v[162:165], 0
	v_mfma_f32_16x16x32_bf16 v[22:25], v[146:149], v[170:173], 0
	v_mfma_f32_16x16x32_bf16 v[18:21], v[154:157], v[170:173], 0
	v_mfma_f32_16x16x32_bf16 v[14:17], v[146:149], v[178:181], 0
	v_mfma_f32_16x16x32_bf16 v[10:13], v[154:157], v[178:181], 0
	v_mfma_f32_16x16x32_bf16 v[6:9], v[146:149], v[186:189], 0
	v_mfma_f32_16x16x32_bf16 v[2:5], v[154:157], v[186:189], 0
	v_mfma_f32_16x16x32_bf16 v[30:33], v[150:153], v[166:169], v[30:33]
	v_mfma_f32_16x16x32_bf16 v[26:29], v[158:161], v[166:169], v[26:29]
	v_mfma_f32_16x16x32_bf16 v[22:25], v[150:153], v[174:177], v[22:25]
	v_mfma_f32_16x16x32_bf16 v[18:21], v[158:161], v[174:177], v[18:21]
	v_mfma_f32_16x16x32_bf16 v[14:17], v[150:153], v[182:185], v[14:17]
	v_mfma_f32_16x16x32_bf16 v[10:13], v[158:161], v[182:185], v[10:13]
	v_mfma_f32_16x16x32_bf16 v[6:9], v[150:153], v[190:193], v[6:9]
	v_mfma_f32_16x16x32_bf16 v[2:5], v[158:161], v[190:193], v[2:5]
	s_setprio 0
	s_barrier
	s_add_i32 s15, 0, 0x18000
	s_add_i32 s46, 0, 0x1c000
	v_add_u32_e32 v142, s15, v211
	v_add_u32_e32 v158, s46, v211
	ds_read_b128 v[130:133], v142
	ds_read_b128 v[134:137], v142 offset:1024
	ds_read_b128 v[138:141], v142 offset:2048
	ds_read_b128 v[142:145], v142 offset:3072
	ds_read_b128 v[146:149], v158
	ds_read_b128 v[150:153], v158 offset:1024
	ds_read_b128 v[154:157], v158 offset:2048
	ds_read_b128 v[158:161], v158 offset:3072
	s_add_u32 s20, s28, 0x20000
	s_addc_u32 s21, s29, 0
	v_mov_b32_e32 v196, v1
	s_mov_b32 m0, s34
	ds_read_b128 v[162:165], v212 offset:32768
	ds_read_b128 v[166:169], v212 offset:33792
	ds_read_b128 v[170:173], v212 offset:34816
	ds_read_b128 v[174:177], v212 offset:35840
	ds_read_b128 v[178:181], v212 offset:36864
	ds_read_b128 v[182:185], v212 offset:37888
	ds_read_b128 v[186:189], v212 offset:38912
	ds_read_b128 v[190:193], v212 offset:39936
	s_nop 0
	global_load_lds_dwordx4 v196, s[20:21]
	v_mov_b32_e32 v196, v208
	s_mov_b32 m0, s35
	s_nop 0
	global_load_lds_dwordx4 v196, s[20:21]
	s_waitcnt vmcnt(8)
	s_waitcnt lgkmcnt(0)
	s_barrier
	s_setprio 1
	s_waitcnt lgkmcnt(0)
	v_mfma_f32_16x16x32_bf16 v[126:129], v[130:133], v[162:165], v[126:129]
	v_mfma_f32_16x16x32_bf16 v[122:125], v[138:141], v[162:165], v[122:125]
	v_mfma_f32_16x16x32_bf16 v[118:121], v[130:133], v[170:173], v[118:121]
	v_mfma_f32_16x16x32_bf16 v[114:117], v[138:141], v[170:173], v[114:117]
	v_mfma_f32_16x16x32_bf16 v[110:113], v[130:133], v[178:181], v[110:113]
	v_mfma_f32_16x16x32_bf16 v[106:109], v[138:141], v[178:181], v[106:109]
	v_mfma_f32_16x16x32_bf16 v[102:105], v[130:133], v[186:189], v[102:105]
	v_mfma_f32_16x16x32_bf16 v[98:101], v[138:141], v[186:189], v[98:101]
	v_mfma_f32_16x16x32_bf16 v[126:129], v[134:137], v[166:169], v[126:129]
	v_mfma_f32_16x16x32_bf16 v[122:125], v[142:145], v[166:169], v[122:125]
	v_mfma_f32_16x16x32_bf16 v[118:121], v[134:137], v[174:177], v[118:121]
	v_mfma_f32_16x16x32_bf16 v[114:117], v[142:145], v[174:177], v[114:117]
	v_mfma_f32_16x16x32_bf16 v[110:113], v[134:137], v[182:185], v[110:113]
	v_mfma_f32_16x16x32_bf16 v[106:109], v[142:145], v[182:185], v[106:109]
	v_mfma_f32_16x16x32_bf16 v[102:105], v[134:137], v[190:193], v[102:105]
	v_mfma_f32_16x16x32_bf16 v[98:101], v[142:145], v[190:193], v[98:101]
	s_setprio 0
	s_setprio 1
	v_mfma_f32_16x16x32_bf16 v[94:97], v[146:149], v[162:165], v[94:97]
	v_mfma_f32_16x16x32_bf16 v[90:93], v[154:157], v[162:165], v[90:93]
	v_mfma_f32_16x16x32_bf16 v[86:89], v[146:149], v[170:173], v[86:89]
	v_mfma_f32_16x16x32_bf16 v[82:85], v[154:157], v[170:173], v[82:85]
	v_mfma_f32_16x16x32_bf16 v[78:81], v[146:149], v[178:181], v[78:81]
	v_mfma_f32_16x16x32_bf16 v[74:77], v[154:157], v[178:181], v[74:77]
	v_mfma_f32_16x16x32_bf16 v[70:73], v[146:149], v[186:189], v[70:73]
	v_mfma_f32_16x16x32_bf16 v[62:65], v[154:157], v[186:189], v[62:65]
	v_mfma_f32_16x16x32_bf16 v[94:97], v[150:153], v[166:169], v[94:97]
	v_mfma_f32_16x16x32_bf16 v[90:93], v[158:161], v[166:169], v[90:93]
	v_mfma_f32_16x16x32_bf16 v[86:89], v[150:153], v[174:177], v[86:89]
	v_mfma_f32_16x16x32_bf16 v[82:85], v[158:161], v[174:177], v[82:85]
	v_mfma_f32_16x16x32_bf16 v[78:81], v[150:153], v[182:185], v[78:81]
	v_mfma_f32_16x16x32_bf16 v[74:77], v[158:161], v[182:185], v[74:77]
	v_mfma_f32_16x16x32_bf16 v[70:73], v[150:153], v[190:193], v[70:73]
	v_mfma_f32_16x16x32_bf16 v[62:65], v[158:161], v[190:193], v[62:65]
	s_setprio 0
	s_barrier
; #define PG8_STAGE(bufoff, gbase, voff) do { const char* gb_ = (const char*)(gbase); asm volatile("" : "+s"(gb_)); _Pragma("unroll") for (int _i = 0; _i < 2; ++_i) { unsigned vo_ = (voff)[_i]; asm volatile("" : "+v"(vo_)); \
;         __builtin_amdgcn_global_load_lds((const unsigned*)(gb_ + vo_), (PG8_LAS unsigned*)(lds + (bufoff) + ldsw + _i * 8192), 16, 0, 0); } } while (0)
; #define PG8_LDA(dst, b, h) do { _Pragma("unroll") for (int m = 0; m < 4; ++m) _Pragma("unroll") for (int k = 0; k < 2; ++k) dst[m][k] = *(const PG8_LAS bf16x8*)(lds + PG8_SA(b, h) + aoff + m * 2048 + k * 1024); } while (0)
; #define PG8_LDB(dst, b, h) do { _Pragma("unroll") for (int n = 0; n < 2; ++n) _Pragma("unroll") for (int k = 0; k < 2; ++k) dst[n][k] = *(const PG8_LAS bf16x8*)(lds + PG8_SB(b, h) + boff + n * 2048 + k * 1024); } while (0)
; #define PG8_MMA(ai, bj, At, Bt) do { __builtin_amdgcn_s_setprio(1); _Pragma("unroll") for (int m = 0; m < 4; ++m) _Pragma("unroll") for (int n = 0; n < 2; ++n) _Pragma("unroll") for (int k = 0; k < 2; ++k) \
;         acc[ai][bj][m][n] = __builtin_amdgcn_mfma_f32_16x16x32_bf16(Bt[n][k], At[m][k], acc[ai][bj][m][n], 0, 0, 0); __builtin_amdgcn_s_setprio(0); } while (0)
; #define PG8_WAIT_V(n) asm volatile("s_waitcnt vmcnt(" #n ")" ::: "memory")
; #define PG8_WAIT_L(n) asm volatile("s_waitcnt lgkmcnt(" #n ")" ::: "memory")
; #define PG8_BAR __builtin_amdgcn_s_barrier()
; #define PG8_SCHED __builtin_amdgcn_sched_barrier(0)
;     ...
;             PG8_LDB(B0, 1, 0); PG8_LDB(B1, 1, 1); PG8_SCHED; PG8_LDA(At, 1, 0); PG8_STAGE(PG8_SA(0, 1), a2 + hstep, voffA);
;             PG8_WAIT_V(8); PG8_WAIT_L(0); PG8_BAR; PG8_MMA(0, 0, At, B0); PG8_MMA(0, 1, At, B1); PG8_BAR; PG8_SCHED;
;             PG8_LDA(At, 1, 1); PG8_STAGE(PG8_SB(1, 0), b3, voffB); PG8_STAGE(PG8_SB(1, 1), b3 + hstepB, voffB); PG8_STAGE(PG8_SA(1, 0), a3, voffA);
;             PG8_WAIT_V(8); PG8_WAIT_L(0); PG8_BAR; PG8_MMA(1, 0, At, B0); PG8_MMA(1, 1, At, B1); PG8_BAR; PG8_SCHED;
	s_add_u32 s20, s26, 0x80
	s_addc_u32 s21, s27, 0
	v_mov_b32_e32 v196, v195
	s_add_i32 s15, s15, s30
	ds_read_b128 v[162:165], v212 offset:49152
	ds_read_b128 v[166:169], v212 offset:50176
	ds_read_b128 v[170:173], v212 offset:51200
	ds_read_b128 v[174:177], v212 offset:52224
	ds_read_b128 v[178:181], v212 offset:53248
	ds_read_b128 v[182:185], v212 offset:54272
	ds_read_b128 v[186:189], v212 offset:55296
	ds_read_b128 v[190:193], v212 offset:56320
	s_mov_b32 m0, s15
	s_nop 0
	global_load_lds_dwordx4 v196, s[20:21]
	v_mov_b32_e32 v196, v209
	s_add_i32 m0, s15, 0x2000
	s_nop 0
	global_load_lds_dwordx4 v196, s[20:21]
	s_add_u32 s20, s26, 0x20080
	s_addc_u32 s21, s27, 0
	v_mov_b32_e32 v196, v195
	s_add_i32 s15, s46, s30
	s_mov_b32 m0, s15
	s_nop 0
	global_load_lds_dwordx4 v196, s[20:21]
	v_mov_b32_e32 v196, v209
	s_add_i32 m0, s15, 0x2000
	s_nop 0
	global_load_lds_dwordx4 v196, s[20:21]
	v_mov_b32_e32 v196, v1
	s_mov_b32 m0, s36
	s_nop 0
	global_load_lds_dwordx4 v196, s[24:25]
	v_mov_b32_e32 v196, v208
	s_mov_b32 m0, s37
	s_nop 0
	global_load_lds_dwordx4 v196, s[24:25]
	s_waitcnt vmcnt(8)
	s_waitcnt lgkmcnt(0)
	s_barrier
	s_setprio 1
	s_waitcnt lgkmcnt(0)
	v_mfma_f32_16x16x32_bf16 v[66:69], v[130:133], v[162:165], v[66:69]
	v_mfma_f32_16x16x32_bf16 v[58:61], v[138:141], v[162:165], v[58:61]
	v_mfma_f32_16x16x32_bf16 v[54:57], v[130:133], v[170:173], v[54:57]
	v_mfma_f32_16x16x32_bf16 v[50:53], v[138:141], v[170:173], v[50:53]
	v_mfma_f32_16x16x32_bf16 v[46:49], v[130:133], v[178:181], v[46:49]
	v_mfma_f32_16x16x32_bf16 v[42:45], v[138:141], v[178:181], v[42:45]
	v_mfma_f32_16x16x32_bf16 v[38:41], v[130:133], v[186:189], v[38:41]
	v_mfma_f32_16x16x32_bf16 v[34:37], v[138:141], v[186:189], v[34:37]
	v_mfma_f32_16x16x32_bf16 v[66:69], v[134:137], v[166:169], v[66:69]
	v_mfma_f32_16x16x32_bf16 v[58:61], v[142:145], v[166:169], v[58:61]
	v_mfma_f32_16x16x32_bf16 v[54:57], v[134:137], v[174:177], v[54:57]
	v_mfma_f32_16x16x32_bf16 v[50:53], v[142:145], v[174:177], v[50:53]
	v_mfma_f32_16x16x32_bf16 v[46:49], v[134:137], v[182:185], v[46:49]
	v_mfma_f32_16x16x32_bf16 v[42:45], v[142:145], v[182:185], v[42:45]
	v_mfma_f32_16x16x32_bf16 v[38:41], v[134:137], v[190:193], v[38:41]
	v_mfma_f32_16x16x32_bf16 v[34:37], v[142:145], v[190:193], v[34:37]
	s_setprio 0
	s_setprio 1
	v_mfma_f32_16x16x32_bf16 v[30:33], v[146:149], v[162:165], v[30:33]
	v_mfma_f32_16x16x32_bf16 v[26:29], v[154:157], v[162:165], v[26:29]
	v_mfma_f32_16x16x32_bf16 v[22:25], v[146:149], v[170:173], v[22:25]
	v_mfma_f32_16x16x32_bf16 v[18:21], v[154:157], v[170:173], v[18:21]
	v_mfma_f32_16x16x32_bf16 v[14:17], v[146:149], v[178:181], v[14:17]
	v_mfma_f32_16x16x32_bf16 v[10:13], v[154:157], v[178:181], v[10:13]
	v_mfma_f32_16x16x32_bf16 v[6:9], v[146:149], v[186:189], v[6:9]
	v_mfma_f32_16x16x32_bf16 v[2:5], v[154:157], v[186:189], v[2:5]
	v_mfma_f32_16x16x32_bf16 v[30:33], v[150:153], v[166:169], v[30:33]
	v_mfma_f32_16x16x32_bf16 v[26:29], v[158:161], v[166:169], v[26:29]
	v_mfma_f32_16x16x32_bf16 v[22:25], v[150:153], v[174:177], v[22:25]
	v_mfma_f32_16x16x32_bf16 v[18:21], v[158:161], v[174:177], v[18:21]
	v_mfma_f32_16x16x32_bf16 v[14:17], v[150:153], v[182:185], v[14:17]
	v_mfma_f32_16x16x32_bf16 v[10:13], v[158:161], v[182:185], v[10:13]
	v_mfma_f32_16x16x32_bf16 v[6:9], v[150:153], v[190:193], v[6:9]
	v_mfma_f32_16x16x32_bf16 v[2:5], v[158:161], v[190:193], v[2:5]
	s_setprio 0
	s_barrier
	s_add_i32 s13, s13, 2
	s_add_u32 s7, s7, 0x100
	s_addc_u32 s11, s11, 0
	s_cmp_gt_u32 s13, 5
	s_mov_b64 s[20:21], s[22:23]
